# grid barrier: last cross-XCD arriver bumps all 16 per-XCD generation words directly; per-leader XCD release add removed (on v030)
# speedup vs baseline: 1.0037x; 1.0037x over previous
; __device__ __forceinline__ unsigned xb_ld(unsigned* p)              { return __hip_atomic_load(p, __ATOMIC_RELAXED, __HIP_MEMORY_SCOPE_AGENT); }
; __device__ __forceinline__ unsigned xb_add(unsigned* p, unsigned v) { return __hip_atomic_fetch_add(p, v, __ATOMIC_RELAXED, __HIP_MEMORY_SCOPE_AGENT); }
; #define XB_SPIN(cond, bar) do { unsigned _sp = 0; while (cond) { __builtin_amdgcn_s_sleep(1); \
;     if ((++_sp & 255u) == 0u) { if (xb_ld(&(bar)[XB_TMO])) break; if (_sp > XB_SPIN_CAP) { atomicAdd(&(bar)[XB_TMO], 1u); break; } } } } while (0)
; __device__ __forceinline__ void xcd_barrier(const XcdBarrier& b) {
;     ...
;         if (old + 1u == (gen + 1u) * nloc) {
;             __builtin_amdgcn_fence(__ATOMIC_RELEASE, "agent");
;             asm volatile("s_waitcnt vmcnt(0)" ::: "memory");
;             const unsigned og = xb_add(&bar[XB_TOP], 1u);
;             const unsigned tg = og / nx;
;             if (og + 1u == (tg + 1u) * nx) xb_add(&bar[XB_TOPGEN], 1u);
;             else XB_SPIN(xb_ld(&bar[XB_TOPGEN]) == tg, bar);
;             asm volatile("" ::: "memory");
;             xb_add(&bar[XB_XGEN(b.x)], 1u);
;             asm volatile("s_waitcnt vmcnt(0)" ::: "memory");
.LBB0_94:
	s_or_b64 exec, exec, s[8:9]
	s_and_saveexec_b64 s[8:9], s[12:13]
	s_cbranch_execz .LBB0_96
	v_mov_b32_e32 v1, 1
	global_atomic_add v[2:3], v1, off
	v_mov_b32_e32 v2, 0
	s_add_u32 s100, s26, 0x702400
	s_addc_u32 s101, s27, 0
	global_atomic_add v2, v1, s[100:101]
	global_atomic_add v2, v1, s[100:101] offset:256
	global_atomic_add v2, v1, s[100:101] offset:512
	global_atomic_add v2, v1, s[100:101] offset:768
	global_atomic_add v2, v1, s[100:101] offset:1024
	global_atomic_add v2, v1, s[100:101] offset:1280
	global_atomic_add v2, v1, s[100:101] offset:1536
	global_atomic_add v2, v1, s[100:101] offset:1792
	global_atomic_add v2, v1, s[100:101] offset:2048
	global_atomic_add v2, v1, s[100:101] offset:2304
	global_atomic_add v2, v1, s[100:101] offset:2560
	global_atomic_add v2, v1, s[100:101] offset:2816
	global_atomic_add v2, v1, s[100:101] offset:3072
	global_atomic_add v2, v1, s[100:101] offset:3328
	global_atomic_add v2, v1, s[100:101] offset:3584
	global_atomic_add v2, v1, s[100:101] offset:3840
.LBB0_96:
	s_or_b64 exec, exec, s[8:9]
	s_mov_b64 s[8:9], exec
	v_mbcnt_lo_u32_b32 v1, s8, 0
	v_mbcnt_hi_u32_b32 v1, s9, v1
	v_cmp_eq_u32_e32 vcc, 0, v1
	s_and_saveexec_b64 s[10:11], vcc
	s_cbranch_execz .LBB0_98
	s_bcnt1_i32_b64 s8, s[8:9]
	v_mov_b32_e32 v1, 0x2000
	v_mov_b32_e32 v2, s8
.LBB0_98:
	s_or_b64 exec, exec, s[10:11]
	s_waitcnt vmcnt(0)

; __device__ __forceinline__ unsigned xb_ld(unsigned* p)              { return __hip_atomic_load(p, __ATOMIC_RELAXED, __HIP_MEMORY_SCOPE_AGENT); }
; __device__ __forceinline__ unsigned xb_add(unsigned* p, unsigned v) { return __hip_atomic_fetch_add(p, v, __ATOMIC_RELAXED, __HIP_MEMORY_SCOPE_AGENT); }
; #define XB_SPIN(cond, bar) do { unsigned _sp = 0; while (cond) { __builtin_amdgcn_s_sleep(1); \
;     if ((++_sp & 255u) == 0u) { if (xb_ld(&(bar)[XB_TMO])) break; if (_sp > XB_SPIN_CAP) { atomicAdd(&(bar)[XB_TMO], 1u); break; } } } } while (0)
; __device__ __forceinline__ void xcd_barrier(const XcdBarrier& b) {
;     ...
;         if (old + 1u == (gen + 1u) * nloc) {
;             __builtin_amdgcn_fence(__ATOMIC_RELEASE, "agent");
;             asm volatile("s_waitcnt vmcnt(0)" ::: "memory");
;             const unsigned og = xb_add(&bar[XB_TOP], 1u);
;             const unsigned tg = og / nx;
;             if (og + 1u == (tg + 1u) * nx) xb_add(&bar[XB_TOPGEN], 1u);
;             else XB_SPIN(xb_ld(&bar[XB_TOPGEN]) == tg, bar);
;             asm volatile("" ::: "memory");
;             xb_add(&bar[XB_XGEN(b.x)], 1u);
;             asm volatile("s_waitcnt vmcnt(0)" ::: "memory");
.LBB0_157:
	s_or_b64 exec, exec, s[8:9]
	s_and_saveexec_b64 s[8:9], s[12:13]
	s_cbranch_execz .LBB0_159
	v_mov_b32_e32 v4, 1
	global_atomic_add v[2:3], v4, off
	v_mov_b32_e32 v2, 0
	s_add_u32 s100, s26, 0x702400
	s_addc_u32 s101, s27, 0
	global_atomic_add v2, v4, s[100:101]
	global_atomic_add v2, v4, s[100:101] offset:256
	global_atomic_add v2, v4, s[100:101] offset:512
	global_atomic_add v2, v4, s[100:101] offset:768
	global_atomic_add v2, v4, s[100:101] offset:1024
	global_atomic_add v2, v4, s[100:101] offset:1280
	global_atomic_add v2, v4, s[100:101] offset:1536
	global_atomic_add v2, v4, s[100:101] offset:1792
	global_atomic_add v2, v4, s[100:101] offset:2048
	global_atomic_add v2, v4, s[100:101] offset:2304
	global_atomic_add v2, v4, s[100:101] offset:2560
	global_atomic_add v2, v4, s[100:101] offset:2816
	global_atomic_add v2, v4, s[100:101] offset:3072
	global_atomic_add v2, v4, s[100:101] offset:3328
	global_atomic_add v2, v4, s[100:101] offset:3584
	global_atomic_add v2, v4, s[100:101] offset:3840
.LBB0_159:
	s_or_b64 exec, exec, s[8:9]
	s_mov_b64 s[8:9], exec
	v_mbcnt_lo_u32_b32 v2, s8, 0
	v_mbcnt_hi_u32_b32 v2, s9, v2
	v_cmp_eq_u32_e32 vcc, 0, v2
	s_and_saveexec_b64 s[10:11], vcc
	s_cbranch_execz .LBB0_161
	s_bcnt1_i32_b64 s8, s[8:9]
	v_mov_b32_e32 v2, 0x2000
	v_mov_b32_e32 v3, s8
.LBB0_161:
	s_or_b64 exec, exec, s[10:11]
	s_waitcnt vmcnt(0)

; __device__ __forceinline__ unsigned xb_ld(unsigned* p)              { return __hip_atomic_load(p, __ATOMIC_RELAXED, __HIP_MEMORY_SCOPE_AGENT); }
; __device__ __forceinline__ unsigned xb_add(unsigned* p, unsigned v) { return __hip_atomic_fetch_add(p, v, __ATOMIC_RELAXED, __HIP_MEMORY_SCOPE_AGENT); }
; #define XB_SPIN(cond, bar) do { unsigned _sp = 0; while (cond) { __builtin_amdgcn_s_sleep(1); \
;     if ((++_sp & 255u) == 0u) { if (xb_ld(&(bar)[XB_TMO])) break; if (_sp > XB_SPIN_CAP) { atomicAdd(&(bar)[XB_TMO], 1u); break; } } } } while (0)
; __device__ __forceinline__ void xcd_barrier(const XcdBarrier& b) {
;     ...
;         if (old + 1u == (gen + 1u) * nloc) {
;             __builtin_amdgcn_fence(__ATOMIC_RELEASE, "agent");
;             asm volatile("s_waitcnt vmcnt(0)" ::: "memory");
;             const unsigned og = xb_add(&bar[XB_TOP], 1u);
;             const unsigned tg = og / nx;
;             if (og + 1u == (tg + 1u) * nx) xb_add(&bar[XB_TOPGEN], 1u);
;             else XB_SPIN(xb_ld(&bar[XB_TOPGEN]) == tg, bar);
;             asm volatile("" ::: "memory");
;             xb_add(&bar[XB_XGEN(b.x)], 1u);
;             asm volatile("s_waitcnt vmcnt(0)" ::: "memory");
.LBB0_488:
	s_or_b64 exec, exec, s[8:9]
	s_mov_b64 s[8:9], exec
	v_mbcnt_lo_u32_b32 v2, s8, 0
	v_mbcnt_hi_u32_b32 v2, s9, v2
	v_cmp_eq_u32_e32 vcc, 0, v2
	s_and_saveexec_b64 s[10:11], vcc
	s_cbranch_execz .LBB0_490
	s_bcnt1_i32_b64 s8, s[8:9]
	v_mov_b32_e32 v2, 0x2000
	v_mov_b32_e32 v3, s8
.LBB0_490:
	s_or_b64 exec, exec, s[10:11]
	s_waitcnt vmcnt(0)

; __device__ __forceinline__ unsigned xb_ld(unsigned* p)              { return __hip_atomic_load(p, __ATOMIC_RELAXED, __HIP_MEMORY_SCOPE_AGENT); }
; __device__ __forceinline__ unsigned xb_add(unsigned* p, unsigned v) { return __hip_atomic_fetch_add(p, v, __ATOMIC_RELAXED, __HIP_MEMORY_SCOPE_AGENT); }
; #define XB_SPIN(cond, bar) do { unsigned _sp = 0; while (cond) { __builtin_amdgcn_s_sleep(1); \
;     if ((++_sp & 255u) == 0u) { if (xb_ld(&(bar)[XB_TMO])) break; if (_sp > XB_SPIN_CAP) { atomicAdd(&(bar)[XB_TMO], 1u); break; } } } } while (0)
; __device__ __forceinline__ void xcd_barrier(const XcdBarrier& b) {
;     ...
;         if (old + 1u == (gen + 1u) * nloc) {
;             __builtin_amdgcn_fence(__ATOMIC_RELEASE, "agent");
;             asm volatile("s_waitcnt vmcnt(0)" ::: "memory");
;             const unsigned og = xb_add(&bar[XB_TOP], 1u);
;             const unsigned tg = og / nx;
;             if (og + 1u == (tg + 1u) * nx) xb_add(&bar[XB_TOPGEN], 1u);
;             else XB_SPIN(xb_ld(&bar[XB_TOPGEN]) == tg, bar);
;             asm volatile("" ::: "memory");
;             xb_add(&bar[XB_XGEN(b.x)], 1u);
;             asm volatile("s_waitcnt vmcnt(0)" ::: "memory");
.LBB0_561:
	s_or_b64 exec, exec, s[8:9]
	s_mov_b64 s[8:9], exec
	v_mbcnt_lo_u32_b32 v2, s8, 0
	v_mbcnt_hi_u32_b32 v2, s9, v2
	v_cmp_eq_u32_e32 vcc, 0, v2
	s_and_saveexec_b64 s[10:11], vcc
	s_cbranch_execz .LBB0_563
	s_bcnt1_i32_b64 s8, s[8:9]
	v_mov_b32_e32 v2, 0x2000
	v_mov_b32_e32 v3, s8
.LBB0_563:
	s_or_b64 exec, exec, s[10:11]
	s_waitcnt vmcnt(0)

; __device__ __forceinline__ unsigned xb_ld(unsigned* p)              { return __hip_atomic_load(p, __ATOMIC_RELAXED, __HIP_MEMORY_SCOPE_AGENT); }
; __device__ __forceinline__ unsigned xb_add(unsigned* p, unsigned v) { return __hip_atomic_fetch_add(p, v, __ATOMIC_RELAXED, __HIP_MEMORY_SCOPE_AGENT); }
; #define XB_SPIN(cond, bar) do { unsigned _sp = 0; while (cond) { __builtin_amdgcn_s_sleep(1); \
;     if ((++_sp & 255u) == 0u) { if (xb_ld(&(bar)[XB_TMO])) break; if (_sp > XB_SPIN_CAP) { atomicAdd(&(bar)[XB_TMO], 1u); break; } } } } while (0)
; __device__ __forceinline__ void xcd_barrier(const XcdBarrier& b) {
;     ...
;         if (old + 1u == (gen + 1u) * nloc) {
;             __builtin_amdgcn_fence(__ATOMIC_RELEASE, "agent");
;             asm volatile("s_waitcnt vmcnt(0)" ::: "memory");
;             const unsigned og = xb_add(&bar[XB_TOP], 1u);
;             const unsigned tg = og / nx;
;             if (og + 1u == (tg + 1u) * nx) xb_add(&bar[XB_TOPGEN], 1u);
;             else XB_SPIN(xb_ld(&bar[XB_TOPGEN]) == tg, bar);
;             asm volatile("" ::: "memory");
;             xb_add(&bar[XB_XGEN(b.x)], 1u);
;             asm volatile("s_waitcnt vmcnt(0)" ::: "memory");
.LBB0_705:
	s_or_b64 exec, exec, s[10:11]
	s_and_saveexec_b64 s[10:11], s[14:15]
	s_cbranch_execz .LBB0_707
	v_mov_b32_e32 v4, 1
	global_atomic_add v[2:3], v4, off
	v_mov_b32_e32 v2, 0
	s_add_u32 s100, s26, 0x702400
	s_addc_u32 s101, s27, 0
	global_atomic_add v2, v4, s[100:101]
	global_atomic_add v2, v4, s[100:101] offset:256
	global_atomic_add v2, v4, s[100:101] offset:512
	global_atomic_add v2, v4, s[100:101] offset:768
	global_atomic_add v2, v4, s[100:101] offset:1024
	global_atomic_add v2, v4, s[100:101] offset:1280
	global_atomic_add v2, v4, s[100:101] offset:1536
	global_atomic_add v2, v4, s[100:101] offset:1792
	global_atomic_add v2, v4, s[100:101] offset:2048
	global_atomic_add v2, v4, s[100:101] offset:2304
	global_atomic_add v2, v4, s[100:101] offset:2560
	global_atomic_add v2, v4, s[100:101] offset:2816
	global_atomic_add v2, v4, s[100:101] offset:3072
	global_atomic_add v2, v4, s[100:101] offset:3328
	global_atomic_add v2, v4, s[100:101] offset:3584
	global_atomic_add v2, v4, s[100:101] offset:3840
.LBB0_707:
	s_or_b64 exec, exec, s[10:11]
	s_mov_b64 s[10:11], exec
	v_mbcnt_lo_u32_b32 v2, s10, 0
	v_mbcnt_hi_u32_b32 v2, s11, v2
	v_cmp_eq_u32_e32 vcc, 0, v2
	s_and_saveexec_b64 s[12:13], vcc
	s_cbranch_execz .LBB0_709
	s_bcnt1_i32_b64 s4, s[10:11]
	v_mov_b32_e32 v2, 0x2000
	v_mov_b32_e32 v3, s4
.LBB0_709:
	s_or_b64 exec, exec, s[12:13]
	s_waitcnt vmcnt(0)

; __device__ __forceinline__ unsigned xb_ld(unsigned* p)              { return __hip_atomic_load(p, __ATOMIC_RELAXED, __HIP_MEMORY_SCOPE_AGENT); }
; __device__ __forceinline__ unsigned xb_add(unsigned* p, unsigned v) { return __hip_atomic_fetch_add(p, v, __ATOMIC_RELAXED, __HIP_MEMORY_SCOPE_AGENT); }
; #define XB_SPIN(cond, bar) do { unsigned _sp = 0; while (cond) { __builtin_amdgcn_s_sleep(1); \
;     if ((++_sp & 255u) == 0u) { if (xb_ld(&(bar)[XB_TMO])) break; if (_sp > XB_SPIN_CAP) { atomicAdd(&(bar)[XB_TMO], 1u); break; } } } } while (0)
; __device__ __forceinline__ void xcd_barrier(const XcdBarrier& b) {
;     ...
;         if (old + 1u == (gen + 1u) * nloc) {
;             __builtin_amdgcn_fence(__ATOMIC_RELEASE, "agent");
;             asm volatile("s_waitcnt vmcnt(0)" ::: "memory");
;             const unsigned og = xb_add(&bar[XB_TOP], 1u);
;             const unsigned tg = og / nx;
;             if (og + 1u == (tg + 1u) * nx) xb_add(&bar[XB_TOPGEN], 1u);
;             else XB_SPIN(xb_ld(&bar[XB_TOPGEN]) == tg, bar);
;             asm volatile("" ::: "memory");
;             xb_add(&bar[XB_XGEN(b.x)], 1u);
;             asm volatile("s_waitcnt vmcnt(0)" ::: "memory");
.LBB0_822:
	s_or_b64 exec, exec, s[10:11]
	s_mov_b64 s[10:11], exec
	v_mbcnt_lo_u32_b32 v2, s10, 0
	v_mbcnt_hi_u32_b32 v2, s11, v2
	v_cmp_eq_u32_e32 vcc, 0, v2
	s_and_saveexec_b64 s[12:13], vcc
	s_cbranch_execz .LBB0_824
	s_bcnt1_i32_b64 s4, s[10:11]
	v_mov_b32_e32 v2, 0x2000
	v_mov_b32_e32 v3, s4
.LBB0_824:
	s_or_b64 exec, exec, s[12:13]
	s_waitcnt vmcnt(0)

; __device__ __forceinline__ unsigned xb_ld(unsigned* p)              { return __hip_atomic_load(p, __ATOMIC_RELAXED, __HIP_MEMORY_SCOPE_AGENT); }
; __device__ __forceinline__ unsigned xb_add(unsigned* p, unsigned v) { return __hip_atomic_fetch_add(p, v, __ATOMIC_RELAXED, __HIP_MEMORY_SCOPE_AGENT); }
; #define XB_SPIN(cond, bar) do { unsigned _sp = 0; while (cond) { __builtin_amdgcn_s_sleep(1); \
;     if ((++_sp & 255u) == 0u) { if (xb_ld(&(bar)[XB_TMO])) break; if (_sp > XB_SPIN_CAP) { atomicAdd(&(bar)[XB_TMO], 1u); break; } } } } while (0)
; __device__ __forceinline__ void xcd_barrier(const XcdBarrier& b) {
;     ...
;         if (old + 1u == (gen + 1u) * nloc) {
;             __builtin_amdgcn_fence(__ATOMIC_RELEASE, "agent");
;             asm volatile("s_waitcnt vmcnt(0)" ::: "memory");
;             const unsigned og = xb_add(&bar[XB_TOP], 1u);
;             const unsigned tg = og / nx;
;             if (og + 1u == (tg + 1u) * nx) xb_add(&bar[XB_TOPGEN], 1u);
;             else XB_SPIN(xb_ld(&bar[XB_TOPGEN]) == tg, bar);
;             asm volatile("" ::: "memory");
;             xb_add(&bar[XB_XGEN(b.x)], 1u);
;             asm volatile("s_waitcnt vmcnt(0)" ::: "memory");
.LBB0_899:
	s_or_b64 exec, exec, s[10:11]
	s_mov_b64 s[10:11], exec
	v_mbcnt_lo_u32_b32 v2, s10, 0
	v_mbcnt_hi_u32_b32 v2, s11, v2
	v_cmp_eq_u32_e32 vcc, 0, v2
	s_and_saveexec_b64 s[12:13], vcc
	s_cbranch_execz .LBB0_901
	s_bcnt1_i32_b64 s4, s[10:11]
	v_mov_b32_e32 v2, 0x2000
	v_mov_b32_e32 v3, s4
.LBB0_901:
	s_or_b64 exec, exec, s[12:13]
	s_waitcnt vmcnt(0)

; __device__ __forceinline__ unsigned xb_ld(unsigned* p)              { return __hip_atomic_load(p, __ATOMIC_RELAXED, __HIP_MEMORY_SCOPE_AGENT); }
; __device__ __forceinline__ unsigned xb_add(unsigned* p, unsigned v) { return __hip_atomic_fetch_add(p, v, __ATOMIC_RELAXED, __HIP_MEMORY_SCOPE_AGENT); }
; #define XB_SPIN(cond, bar) do { unsigned _sp = 0; while (cond) { __builtin_amdgcn_s_sleep(1); \
;     if ((++_sp & 255u) == 0u) { if (xb_ld(&(bar)[XB_TMO])) break; if (_sp > XB_SPIN_CAP) { atomicAdd(&(bar)[XB_TMO], 1u); break; } } } } while (0)
; __device__ __forceinline__ void xcd_barrier(const XcdBarrier& b) {
;     ...
;         if (old + 1u == (gen + 1u) * nloc) {
;             __builtin_amdgcn_fence(__ATOMIC_RELEASE, "agent");
;             asm volatile("s_waitcnt vmcnt(0)" ::: "memory");
;             const unsigned og = xb_add(&bar[XB_TOP], 1u);
;             const unsigned tg = og / nx;
;             if (og + 1u == (tg + 1u) * nx) xb_add(&bar[XB_TOPGEN], 1u);
;             else XB_SPIN(xb_ld(&bar[XB_TOPGEN]) == tg, bar);
;             asm volatile("" ::: "memory");
;             xb_add(&bar[XB_XGEN(b.x)], 1u);
;             asm volatile("s_waitcnt vmcnt(0)" ::: "memory");
.LBB0_1062:
	s_or_b64 exec, exec, s[10:11]
	s_mov_b64 s[10:11], exec
	v_mbcnt_lo_u32_b32 v2, s10, 0
	v_mbcnt_hi_u32_b32 v2, s11, v2
	v_cmp_eq_u32_e32 vcc, 0, v2
	s_and_saveexec_b64 s[12:13], vcc
	s_cbranch_execz .LBB0_1064
	s_bcnt1_i32_b64 s4, s[10:11]
	v_mov_b32_e32 v2, 0x2000
	v_mov_b32_e32 v3, s4
.LBB0_1064:
	s_or_b64 exec, exec, s[12:13]
	s_waitcnt vmcnt(0)

; __device__ __forceinline__ unsigned xb_ld(unsigned* p)              { return __hip_atomic_load(p, __ATOMIC_RELAXED, __HIP_MEMORY_SCOPE_AGENT); }
; __device__ __forceinline__ unsigned xb_add(unsigned* p, unsigned v) { return __hip_atomic_fetch_add(p, v, __ATOMIC_RELAXED, __HIP_MEMORY_SCOPE_AGENT); }
; #define XB_SPIN(cond, bar) do { unsigned _sp = 0; while (cond) { __builtin_amdgcn_s_sleep(1); \
;     if ((++_sp & 255u) == 0u) { if (xb_ld(&(bar)[XB_TMO])) break; if (_sp > XB_SPIN_CAP) { atomicAdd(&(bar)[XB_TMO], 1u); break; } } } } while (0)
; __device__ __forceinline__ void xcd_barrier(const XcdBarrier& b) {
;     ...
;         if (old + 1u == (gen + 1u) * nloc) {
;             __builtin_amdgcn_fence(__ATOMIC_RELEASE, "agent");
;             asm volatile("s_waitcnt vmcnt(0)" ::: "memory");
;             const unsigned og = xb_add(&bar[XB_TOP], 1u);
;             const unsigned tg = og / nx;
;             if (og + 1u == (tg + 1u) * nx) xb_add(&bar[XB_TOPGEN], 1u);
;             else XB_SPIN(xb_ld(&bar[XB_TOPGEN]) == tg, bar);
;             asm volatile("" ::: "memory");
;             xb_add(&bar[XB_XGEN(b.x)], 1u);
;             asm volatile("s_waitcnt vmcnt(0)" ::: "memory");
.LBB0_1391:
	s_or_b64 exec, exec, s[10:11]
	s_mov_b64 s[10:11], exec
	v_mbcnt_lo_u32_b32 v2, s10, 0
	v_mbcnt_hi_u32_b32 v2, s11, v2
	v_cmp_eq_u32_e32 vcc, 0, v2
	s_and_saveexec_b64 s[12:13], vcc
	s_cbranch_execz .LBB0_1393
	s_bcnt1_i32_b64 s4, s[10:11]
	v_mov_b32_e32 v2, 0x2000
	v_mov_b32_e32 v3, s4
.LBB0_1393:
	s_or_b64 exec, exec, s[12:13]
	s_waitcnt vmcnt(0)

; __device__ __forceinline__ unsigned xb_ld(unsigned* p)              { return __hip_atomic_load(p, __ATOMIC_RELAXED, __HIP_MEMORY_SCOPE_AGENT); }
; __device__ __forceinline__ unsigned xb_add(unsigned* p, unsigned v) { return __hip_atomic_fetch_add(p, v, __ATOMIC_RELAXED, __HIP_MEMORY_SCOPE_AGENT); }
; #define XB_SPIN(cond, bar) do { unsigned _sp = 0; while (cond) { __builtin_amdgcn_s_sleep(1); \
;     if ((++_sp & 255u) == 0u) { if (xb_ld(&(bar)[XB_TMO])) break; if (_sp > XB_SPIN_CAP) { atomicAdd(&(bar)[XB_TMO], 1u); break; } } } } while (0)
; __device__ __forceinline__ void xcd_barrier(const XcdBarrier& b) {
;     ...
;         if (old + 1u == (gen + 1u) * nloc) {
;             __builtin_amdgcn_fence(__ATOMIC_RELEASE, "agent");
;             asm volatile("s_waitcnt vmcnt(0)" ::: "memory");
;             const unsigned og = xb_add(&bar[XB_TOP], 1u);
;             const unsigned tg = og / nx;
;             if (og + 1u == (tg + 1u) * nx) xb_add(&bar[XB_TOPGEN], 1u);
;             else XB_SPIN(xb_ld(&bar[XB_TOPGEN]) == tg, bar);
;             asm volatile("" ::: "memory");
;             xb_add(&bar[XB_XGEN(b.x)], 1u);
;             asm volatile("s_waitcnt vmcnt(0)" ::: "memory");
.LBB0_1464:
	s_or_b64 exec, exec, s[10:11]
	s_mov_b64 s[10:11], exec
	v_mbcnt_lo_u32_b32 v2, s10, 0
	v_mbcnt_hi_u32_b32 v2, s11, v2
	v_cmp_eq_u32_e32 vcc, 0, v2
	s_and_saveexec_b64 s[12:13], vcc
	s_cbranch_execz .LBB0_1466
	s_bcnt1_i32_b64 s4, s[10:11]
	v_mov_b32_e32 v2, 0x2000
	v_mov_b32_e32 v3, s4
.LBB0_1466:
	s_or_b64 exec, exec, s[12:13]
	s_waitcnt vmcnt(0)

; __device__ __forceinline__ unsigned xb_ld(unsigned* p)              { return __hip_atomic_load(p, __ATOMIC_RELAXED, __HIP_MEMORY_SCOPE_AGENT); }
; __device__ __forceinline__ unsigned xb_add(unsigned* p, unsigned v) { return __hip_atomic_fetch_add(p, v, __ATOMIC_RELAXED, __HIP_MEMORY_SCOPE_AGENT); }
; #define XB_SPIN(cond, bar) do { unsigned _sp = 0; while (cond) { __builtin_amdgcn_s_sleep(1); \
;     if ((++_sp & 255u) == 0u) { if (xb_ld(&(bar)[XB_TMO])) break; if (_sp > XB_SPIN_CAP) { atomicAdd(&(bar)[XB_TMO], 1u); break; } } } } while (0)
; __device__ __forceinline__ void xcd_barrier(const XcdBarrier& b) {
;     ...
;         if (old + 1u == (gen + 1u) * nloc) {
;             __builtin_amdgcn_fence(__ATOMIC_RELEASE, "agent");
;             asm volatile("s_waitcnt vmcnt(0)" ::: "memory");
;             const unsigned og = xb_add(&bar[XB_TOP], 1u);
;             const unsigned tg = og / nx;
;             if (og + 1u == (tg + 1u) * nx) xb_add(&bar[XB_TOPGEN], 1u);
;             else XB_SPIN(xb_ld(&bar[XB_TOPGEN]) == tg, bar);
;             asm volatile("" ::: "memory");
;             xb_add(&bar[XB_XGEN(b.x)], 1u);
;             asm volatile("s_waitcnt vmcnt(0)" ::: "memory");
.LBB0_1610:
	s_or_b64 exec, exec, s[10:11]
	s_mov_b64 s[10:11], exec
	v_mbcnt_lo_u32_b32 v2, s10, 0
	v_mbcnt_hi_u32_b32 v2, s11, v2
	v_cmp_eq_u32_e32 vcc, 0, v2
	s_and_saveexec_b64 s[12:13], vcc
	s_cbranch_execz .LBB0_1612
	s_bcnt1_i32_b64 s4, s[10:11]
	v_mov_b32_e32 v2, 0x2000
	v_mov_b32_e32 v3, s4
.LBB0_1612:
	s_or_b64 exec, exec, s[12:13]
	s_waitcnt vmcnt(0)

; __device__ __forceinline__ unsigned xb_ld(unsigned* p)              { return __hip_atomic_load(p, __ATOMIC_RELAXED, __HIP_MEMORY_SCOPE_AGENT); }
; __device__ __forceinline__ unsigned xb_add(unsigned* p, unsigned v) { return __hip_atomic_fetch_add(p, v, __ATOMIC_RELAXED, __HIP_MEMORY_SCOPE_AGENT); }
; #define XB_SPIN(cond, bar) do { unsigned _sp = 0; while (cond) { __builtin_amdgcn_s_sleep(1); \
;     if ((++_sp & 255u) == 0u) { if (xb_ld(&(bar)[XB_TMO])) break; if (_sp > XB_SPIN_CAP) { atomicAdd(&(bar)[XB_TMO], 1u); break; } } } } while (0)
; __device__ __forceinline__ void xcd_barrier(const XcdBarrier& b) {
;     ...
;         if (old + 1u == (gen + 1u) * nloc) {
;             __builtin_amdgcn_fence(__ATOMIC_RELEASE, "agent");
;             asm volatile("s_waitcnt vmcnt(0)" ::: "memory");
;             const unsigned og = xb_add(&bar[XB_TOP], 1u);
;             const unsigned tg = og / nx;
;             if (og + 1u == (tg + 1u) * nx) xb_add(&bar[XB_TOPGEN], 1u);
;             else XB_SPIN(xb_ld(&bar[XB_TOPGEN]) == tg, bar);
;             asm volatile("" ::: "memory");
;             xb_add(&bar[XB_XGEN(b.x)], 1u);
;             asm volatile("s_waitcnt vmcnt(0)" ::: "memory");
.LBB0_1725:
	s_or_b64 exec, exec, s[10:11]
	s_mov_b64 s[10:11], exec
	v_mbcnt_lo_u32_b32 v2, s10, 0
	v_mbcnt_hi_u32_b32 v2, s11, v2
	v_cmp_eq_u32_e32 vcc, 0, v2
	s_and_saveexec_b64 s[12:13], vcc
	s_cbranch_execz .LBB0_1727
	s_bcnt1_i32_b64 s4, s[10:11]
	v_mov_b32_e32 v2, 0x2000
	v_mov_b32_e32 v3, s4
.LBB0_1727:
	s_or_b64 exec, exec, s[12:13]
	s_waitcnt vmcnt(0)

; __device__ __forceinline__ unsigned xb_ld(unsigned* p)              { return __hip_atomic_load(p, __ATOMIC_RELAXED, __HIP_MEMORY_SCOPE_AGENT); }
; __device__ __forceinline__ unsigned xb_add(unsigned* p, unsigned v) { return __hip_atomic_fetch_add(p, v, __ATOMIC_RELAXED, __HIP_MEMORY_SCOPE_AGENT); }
; #define XB_SPIN(cond, bar) do { unsigned _sp = 0; while (cond) { __builtin_amdgcn_s_sleep(1); \
;     if ((++_sp & 255u) == 0u) { if (xb_ld(&(bar)[XB_TMO])) break; if (_sp > XB_SPIN_CAP) { atomicAdd(&(bar)[XB_TMO], 1u); break; } } } } while (0)
; __device__ __forceinline__ void xcd_barrier(const XcdBarrier& b) {
;     ...
;         if (old + 1u == (gen + 1u) * nloc) {
;             __builtin_amdgcn_fence(__ATOMIC_RELEASE, "agent");
;             asm volatile("s_waitcnt vmcnt(0)" ::: "memory");
;             const unsigned og = xb_add(&bar[XB_TOP], 1u);
;             const unsigned tg = og / nx;
;             if (og + 1u == (tg + 1u) * nx) xb_add(&bar[XB_TOPGEN], 1u);
;             else XB_SPIN(xb_ld(&bar[XB_TOPGEN]) == tg, bar);
;             asm volatile("" ::: "memory");
;             xb_add(&bar[XB_XGEN(b.x)], 1u);
;             asm volatile("s_waitcnt vmcnt(0)" ::: "memory");
.LBB0_1802:
	s_or_b64 exec, exec, s[10:11]
	s_mov_b64 s[10:11], exec
	v_mbcnt_lo_u32_b32 v2, s10, 0
	v_mbcnt_hi_u32_b32 v2, s11, v2
	v_cmp_eq_u32_e32 vcc, 0, v2
	s_and_saveexec_b64 s[12:13], vcc
	s_cbranch_execz .LBB0_1804
	s_bcnt1_i32_b64 s4, s[10:11]
	v_mov_b32_e32 v2, 0x2000
	v_mov_b32_e32 v3, s4
.LBB0_1804:
	s_or_b64 exec, exec, s[12:13]
	s_waitcnt vmcnt(0)
